# staggered start of workgroup groups in the branch GEMM phase to spread the synchronized gate-load bursts
# baseline (speedup 1.0000x reference)
;     __device__ bool next(int i, Unit& u) const {
;         const long L = (long)i * G + c; if (L >= nwg) return false;
;         int wgid = (int)L; { const int q = nwg / NXCD, r = nwg % NXCD, xcd = wgid % NXCD, off = wgid / NXCD; wgid = (xcd < r ? xcd * (q + 1) : r * (q + 1) + (xcd - r) * q) + off; }
; template <class Epi, class Sched>
; __device__ __forceinline__ void gemm_phase(LAS unsigned char* lds, const Gemm g, const Sched& S, const Epi& E, const int tid) {
;     ...
;     Unit cur, nxt; int ui = 0;
;     if (!S.next(0, cur)) return;
.LBB0_153:
	v_mov_b32_e32 v16, v225
	s_mov_b32 s17, s78
	s_mov_b32 s25, s68
	s_mov_b32 s8, s29
	s_cmpk_gt_i32 s25, 0x1ff
	v_readfirstlane_b32 s15, v16
	s_cbranch_scc1 .LBB0_187
	s_lshr_b32 s0, s25, 3
	s_and_b32 s0, s0, 3
.Lstg_branch_loop:
	s_cmp_eq_u32 s0, 0
	s_cbranch_scc1 .Lstg_branch_done
	s_sleep 100
	s_sub_u32 s0, s0, 1
	s_branch .Lstg_branch_loop
.Lstg_branch_done:
	s_ashr_i32 s27, s25, 31
	s_lshr_b32 s0, s27, 29
	s_add_i32 s3, s25, s0
	s_and_b32 s0, s3, -8
	s_sub_i32 s9, s25, s0
	s_cmp_gt_i32 s9, -1
	s_mov_b64 s[0:1], -1
	s_cbranch_scc0 .LBB0_156
	s_lshl_b32 s2, s9, 6
	s_mov_b64 s[0:1], 0
